# split-phase grid barrier 4 for the 64 P4 GEMM workgroups: arrive only, completion wait deferred to just before the GEMM epilogue stores
# speedup vs baseline: 1.0133x; 1.0133x over previous
; __device__ __forceinline__ unsigned xb_ld(unsigned* p)              { return __hip_atomic_load(p, __ATOMIC_RELAXED, __HIP_MEMORY_SCOPE_AGENT); }
; __device__ __forceinline__ unsigned xb_add(unsigned* p, unsigned v) { return __hip_atomic_fetch_add(p, v, __ATOMIC_RELAXED, __HIP_MEMORY_SCOPE_AGENT); }
; #define XB_SPIN(cond, bar) do { unsigned _sp = 0; while (cond) { __builtin_amdgcn_s_sleep(1); \
;     if ((++_sp & 255u) == 0u) { if (xb_ld(&(bar)[XB_TMO])) break; if (_sp > XB_SPIN_CAP) { atomicAdd(&(bar)[XB_TMO], 1u); break; } } } } while (0)
; __device__ __forceinline__ void xcd_barrier(const XcdBarrier& b) {
;     ...
;         const unsigned old = xb_add(&bar[XB_XSUB(b.x)], 1u);
;         const unsigned gen = old / nloc;
;         if (old + 1u == (gen + 1u) * nloc) {
;             __builtin_amdgcn_fence(__ATOMIC_RELEASE, "agent");
;             asm volatile("s_waitcnt vmcnt(0)" ::: "memory");
;             const unsigned og = xb_add(&bar[XB_TOP], 1u);
;             const unsigned tg = og / nx;
;             if (og + 1u == (tg + 1u) * nx) xb_add(&bar[XB_TOPGEN], 1u);
;             else XB_SPIN(xb_ld(&bar[XB_TOPGEN]) == tg, bar);
;             __builtin_amdgcn_fence(__ATOMIC_ACQUIRE, "agent");
;             xb_add(&bar[XB_XGEN(b.x)], 1u);
;             asm volatile("s_waitcnt vmcnt(0)" ::: "memory");
;         } else {
;             XB_SPIN(xb_ld(&bar[XB_XGEN(b.x)]) == gen, bar);
;             __builtin_amdgcn_fence(__ATOMIC_ACQUIRE, "agent");
.LBB0_693:
	s_or_b64 exec, exec, s[8:9]
	v_cvt_f32_u32_e32 v4, v2
	s_waitcnt vmcnt(0)
	v_readfirstlane_b32 s3, v3
	v_sub_u32_e32 v3, 0, v2
	v_rcp_iflag_f32_e32 v4, v4
	v_add_u32_e32 v5, s3, v1
	v_mul_f32_e32 v4, 0x4f7ffffe, v4
	v_cvt_u32_f32_e32 v4, v4
	v_mul_lo_u32 v1, v3, v4
	v_mul_hi_u32 v1, v4, v1
	v_add_u32_e32 v1, v4, v1
	v_mul_hi_u32 v1, v5, v1
	v_mul_lo_u32 v3, v1, v2
	v_sub_u32_e32 v3, v5, v3
	v_add_u32_e32 v4, 1, v1
	v_cmp_ge_u32_e32 vcc, v3, v2
	s_nop 1
	v_cndmask_b32_e32 v1, v1, v4, vcc
	v_sub_u32_e32 v4, v3, v2
	v_cndmask_b32_e32 v3, v3, v4, vcc
	v_add_u32_e32 v4, 1, v1
	v_cmp_ge_u32_e32 vcc, v3, v2
	v_add_u32_e32 v3, 1, v5
	s_nop 0
	v_cndmask_b32_e32 v1, v1, v4, vcc
	v_mul_lo_u32 v4, v2, v1
	v_add_u32_e32 v2, v4, v2
	v_cmp_ne_u32_e32 vcc, v3, v2
	s_and_saveexec_b64 s[6:7], vcc
	s_xor_b64 s[6:7], exec, s[6:7]
	s_cbranch_execz .LBB0_707
	s_and_b64 s[8:9], s[78:79], exec
	s_cbranch_scc0 .Lsp4_norm
	s_cmpk_gt_u32 s2, 63
	s_cbranch_scc1 .Lsp4_norm
	v_readfirstlane_b32 s101, v1
	s_mov_b32 s99, 0x4444
	s_branch .LBB0_707
.Lsp4_norm:
	s_waitcnt lgkmcnt(0)
	buffer_inv sc1
	v_mov_b32_e32 v0, 0x2000
	global_load_dword v0, v0, s[4:5] offset:1024 sc1
	s_add_u32 s12, s4, 0x2400
	s_addc_u32 s13, s5, 0
	s_waitcnt vmcnt(0)
	v_cmp_eq_u32_e32 vcc, v0, v1
	s_and_saveexec_b64 s[8:9], vcc
	s_cbranch_execz .LBB0_706
	s_add_u32 s10, s68, 0x80200
	s_addc_u32 s11, s69, 0
	s_mov_b32 s3, 1
	s_mov_b64 s[14:15], 0
	v_mov_b32_e32 v0, 0
	s_branch .LBB0_697

;     __device__ __forceinline__ void operator()(const f32x4 (&acc)[2][2][4][2], const Unit& u, int wr, int wc, int fr, int fq) const {
;         float rsv[8];
; #pragma unroll
;         for (int idx = 0; idx < 8; ++idx) { const f32x4 q = *(const f32x4*)(rowss + (size_t)(u.pm * BM + (idx >> 2) * HALF + wr * 64 + (idx & 3) * 16 + fr) * 4); rsv[idx] = (q[0] + q[1]) + (q[2] + q[3]); }
; #pragma unroll
;         for (int ai = 0; ai < 2; ++ai)
; #pragma unroll
;             for (int m = 0; m < 4; ++m) {
;                 const int r = u.pm * BM + ai * HALF + wr * 64 + m * 16 + fr;
;                 const float rs = rsqrtf(rsv[ai * 4 + m] * (1.0f / DM) + EPS);
; #pragma unroll
;                 for (int bj = 0; bj < 2; ++bj) {
;                     f32x4 a = acc[ai][bj][m][0] * rs, b = acc[ai][bj][m][1] * rs;
; #pragma unroll
;                     for (int t = 0; t < 4; ++t) { a[t] = fmaxf(a[t], 0.f); a[t] *= a[t]; b[t] = fmaxf(b[t], 0.f); b[t] *= b[t]; }
;                     st8bf(U + (size_t)r * FF + u.pn * BM + wc * 64 + bj * 32 + 8 * fq, a, b);
.LBB0_761:
	s_cmp_eq_u32 s99, 0x4444
	s_cbranch_scc0 .Lsp4_nowait
	s_mov_b32 s99, 0
	s_mov_b64 exec, 1
	s_lshl_b32 s98, s33, 8
	s_add_u32 s98, s98, 0x82400
	v_mov_b32_e32 v228, s98
	v_mov_b32_e32 v230, s101
	s_mov_b32 s98, 0x40000
.Lsp4_poll:
	global_load_dword v229, v228, s[68:69] sc1
	s_waitcnt vmcnt(0)
	v_cmp_ne_u32_e32 vcc, v229, v230
	s_cbranch_vccnz .Lsp4_done
	s_sleep 1
	s_sub_u32 s98, s98, 1
	s_cmp_eq_u32 s98, 0
	s_cbranch_scc0 .Lsp4_poll
.Lsp4_done:
	buffer_inv sc1
	s_waitcnt vmcnt(0)
	s_mov_b64 exec, -1
.Lsp4_nowait:
	s_barrier
	s_add_u32 s6, s68, 0x120000
	v_lshl_add_u32 v130, s4, 8, v129
	s_addc_u32 s7, s69, 0
	v_ashrrev_i32_e32 v131, 31, v130
	v_or_b32_e32 v148, 16, v130
	v_lshl_add_u64 v[132:133], v[130:131], 4, s[6:7]
	v_ashrrev_i32_e32 v149, 31, v148
	v_or_b32_e32 v146, 32, v130
	v_lshl_add_u64 v[138:139], v[148:149], 4, s[6:7]
	global_load_dwordx4 v[134:137], v[132:133], off
	global_load_dwordx4 v[142:145], v[138:139], off
	v_ashrrev_i32_e32 v147, 31, v146
	v_or_b32_e32 v140, 48, v130
	v_lshl_add_u64 v[132:133], v[146:147], 4, s[6:7]
	v_ashrrev_i32_e32 v141, 31, v140
	v_lshl_add_u64 v[138:139], v[140:141], 4, s[6:7]
	global_load_dwordx4 v[150:153], v[132:133], off
	global_load_dwordx4 v[154:157], v[138:139], off
	v_add_u32_e32 v138, 0x80, v130
	v_add_u32_e32 v158, 0x90, v130
	v_ashrrev_i32_e32 v139, 31, v138
	v_ashrrev_i32_e32 v159, 31, v158
	v_lshl_add_u64 v[132:133], v[138:139], 4, s[6:7]
	v_lshl_add_u64 v[162:163], v[158:159], 4, s[6:7]
	global_load_dwordx4 v[158:161], v[132:133], off
	s_nop 0
	global_load_dwordx4 v[162:165], v[162:163], off
	v_add_u32_e32 v132, 0xa0, v130
	v_ashrrev_i32_e32 v133, 31, v132
	v_lshl_add_u64 v[132:133], v[132:133], 4, s[6:7]
	global_load_dwordx4 v[166:169], v[132:133], off
	v_add_u32_e32 v132, 0xb0, v130
	v_ashrrev_i32_e32 v133, 31, v132
	v_lshl_add_u64 v[132:133], v[132:133], 4, s[6:7]
	s_mov_b32 s8, 0x358637bd
	global_load_dwordx4 v[170:173], v[132:133], off
	s_mov_b32 s4, 0x3a800000
	s_mov_b32 s5, 0x800000
	v_mov_b64_e32 v[132:133], s[8:9]
	s_add_u32 s10, s68, 0x3200000
	s_addc_u32 s11, s69, 0
	s_lshl_b32 s8, s0, 8
	v_lshlrev_b64 v[130:131], 13, v[130:131]
	s_ashr_i32 s9, s8, 31
	v_lshl_add_u64 v[130:131], s[10:11], 0, v[130:131]
	s_lshl_b64 s[8:9], s[8:9], 1
	s_mov_b32 s1, 0
	s_lshl_b32 s0, s48, 7
	v_lshl_add_u64 v[130:131], v[130:131], 0, s[8:9]
	v_mov_b32_e32 v129, 0
	v_lshl_add_u64 v[130:131], v[130:131], 0, s[0:1]
	v_lshl_add_u64 v[130:131], v[130:131], 0, v[128:129]
	s_mov_b64 s[6:7], 0x120000
	s_waitcnt vmcnt(0)
	v_mov_b32_e32 v176, v135
	v_mov_b32_e32 v177, v136
	v_mov_b32_e32 v135, v137
	v_mov_b32_e32 v136, v143
	v_mov_b32_e32 v137, v144
	v_mov_b32_e32 v143, v145
	v_pk_add_f32 v[134:135], v[176:177], v[134:135]
	v_mov_b32_e32 v144, v151
	v_mov_b32_e32 v145, v152
	v_mov_b32_e32 v151, v153
	v_pk_add_f32 v[136:137], v[136:137], v[142:143]
	v_pk_add_f32 v[150:151], v[144:145], v[150:151]
	v_mov_b32_e32 v145, v134
	v_mov_b32_e32 v144, v136
	v_mov_b32_e32 v134, v137
	v_mov_b32_e32 v152, v155
	v_mov_b32_e32 v153, v156
	v_mov_b32_e32 v155, v157
	v_pk_add_f32 v[134:135], v[144:145], v[134:135]
	v_pk_add_f32 v[152:153], v[152:153], v[154:155]
	v_pk_fma_f32 v[154:155], v[134:135], s[4:5], v[132:133] op_sel_hi:[1,0,0]
	v_mov_b32_e32 v156, v159
	v_mul_f32_e32 v134, 0x4b800000, v155
	v_cmp_gt_f32_e32 vcc, s5, v155
	v_mov_b32_e32 v157, v160
	v_mov_b32_e32 v159, v161
	v_cndmask_b32_e32 v134, v155, v134, vcc
	v_rsq_f32_e32 v155, v134
	v_pk_add_f32 v[142:143], v[156:157], v[158:159]
	v_mov_b32_e32 v160, v163
	v_mov_b32_e32 v161, v164
	v_mul_f32_e32 v156, 0x45800000, v155
	v_cndmask_b32_e32 v156, v155, v156, vcc
	v_pk_mul_f32 v[120:121], v[120:121], v[156:157] op_sel_hi:[1,0]
	v_pk_mul_f32 v[126:127], v[126:127], v[156:157] op_sel_hi:[1,0]
	v_pk_mul_f32 v[124:125], v[124:125], v[156:157] op_sel_hi:[1,0]
	v_pk_mul_f32 v[122:123], v[122:123], v[156:157] op_sel_hi:[1,0]
	v_max_f32_e32 v120, 0, v120
	v_max_f32_e32 v121, 0, v121
	v_mov_b32_e32 v163, v165
	v_max_f32_e32 v124, 0, v124
	v_max_f32_e32 v125, 0, v125
	v_pk_mul_f32 v[158:159], v[120:121], v[120:121]
	v_max_f32_e32 v120, 0, v126
	v_max_f32_e32 v122, 0, v122
	v_max_f32_e32 v121, 0, v127
	v_max_f32_e32 v123, 0, v123
	v_pk_add_f32 v[144:145], v[160:161], v[162:163]
	v_pk_mul_f32 v[124:125], v[124:125], v[124:125]
	v_pk_mul_f32 v[126:127], v[120:121], v[120:121]
	v_pk_mul_f32 v[160:161], v[122:123], v[122:123]
	v_pk_mul_f32 v[114:115], v[114:115], v[156:157] op_sel_hi:[1,0]
	v_cvt_pk_bf16_f32 v120, v124, v125
	v_cvt_pk_bf16_f32 v121, v126, v127
	v_cvt_pk_bf16_f32 v122, v158, v159
	v_cvt_pk_bf16_f32 v123, v160, v161
	v_pk_mul_f32 v[116:117], v[116:117], v[156:157] op_sel_hi:[1,0]
	v_pk_mul_f32 v[112:113], v[112:113], v[156:157] op_sel_hi:[1,0]
	v_max_f32_e32 v114, 0, v114
	v_max_f32_e32 v115, 0, v115
	global_store_dwordx4 v[130:131], v[120:123], off
	v_pk_mul_f32 v[118:119], v[118:119], v[156:157] op_sel_hi:[1,0]
	v_max_f32_e32 v116, 0, v116
	v_max_f32_e32 v112, 0, v112
	v_max_f32_e32 v117, 0, v117
	v_max_f32_e32 v113, 0, v113
	v_pk_mul_f32 v[122:123], v[114:115], v[114:115]
	v_mul_f32_e32 v114, 0x4b800000, v154
	v_cmp_gt_f32_e32 vcc, s5, v154
	v_pk_mul_f32 v[116:117], v[116:117], v[116:117]
	v_pk_mul_f32 v[120:121], v[112:113], v[112:113]
	v_max_f32_e32 v112, 0, v118
	v_max_f32_e32 v113, 0, v119
	v_cndmask_b32_e32 v114, v154, v114, vcc
	v_pk_mul_f32 v[118:119], v[112:113], v[112:113]
	v_cvt_pk_bf16_f32 v112, v116, v117
	v_rsq_f32_e32 v116, v114
	v_cvt_pk_bf16_f32 v113, v118, v119
	v_cvt_pk_bf16_f32 v114, v120, v121
	v_cvt_pk_bf16_f32 v115, v122, v123
	global_store_dwordx4 v[130:131], v[112:115], off offset:64
	v_mov_b32_e32 v164, v167
;     __device__ __forceinline__ void operator()(const f32x4 (&acc)[2][2][4][2], const Unit& u, int wr, int wc, int fr, int fq) const {
;     ...
;         for (int idx = 0; idx < 8; ++idx) { const f32x4 q = *(const f32x4*)(rowss + (size_t)(u.pm * BM + (idx >> 2) * HALF + wr * 64 + (idx & 3) * 16 + fr) * 4); rsv[idx] = (q[0] + q[1]) + (q[2] + q[3]); }
; #pragma unroll
;         for (int ai = 0; ai < 2; ++ai)
; #pragma unroll
;             for (int m = 0; m < 4; ++m) {
;                 const int r = u.pm * BM + ai * HALF + wr * 64 + m * 16 + fr;
;                 const float rs = rsqrtf(rsv[ai * 4 + m] * (1.0f / DM) + EPS);
; #pragma unroll
;                 for (int bj = 0; bj < 2; ++bj) {
;                     f32x4 a = acc[ai][bj][m][0] * rs, b = acc[ai][bj][m][1] * rs;
; #pragma unroll
;                     for (int t = 0; t < 4; ++t) { a[t] = fmaxf(a[t], 0.f); a[t] *= a[t]; b[t] = fmaxf(b[t], 0.f); b[t] *= b[t]; }
;                     st8bf(U + (size_t)r * FF + u.pn * BM + wc * 64 + bj * 32 + 8 * fq, a, b);
;                 }
;             }
	v_mov_b32_e32 v165, v168
	v_mul_f32_e32 v112, 0x45800000, v116
	v_cndmask_b32_e32 v112, v116, v112, vcc
	v_pk_mul_f32 v[104:105], v[104:105], v[112:113] op_sel_hi:[1,0]
	v_pk_mul_f32 v[110:111], v[110:111], v[112:113] op_sel_hi:[1,0]
	v_max_f32_e32 v104, 0, v104
	v_max_f32_e32 v105, 0, v105
	v_lshlrev_b64 v[114:115], 13, v[148:149]
	v_pk_mul_f32 v[116:117], v[104:105], v[104:105]
	v_max_f32_e32 v104, 0, v110
	v_max_f32_e32 v105, 0, v111
	v_pk_mul_f32 v[108:109], v[108:109], v[112:113] op_sel_hi:[1,0]
	v_pk_mul_f32 v[106:107], v[106:107], v[112:113] op_sel_hi:[1,0]
	v_pk_mul_f32 v[110:111], v[104:105], v[104:105]
	v_lshl_add_u64 v[104:105], s[10:11], 0, v[114:115]
	v_max_f32_e32 v108, 0, v108
	v_max_f32_e32 v109, 0, v109
	v_max_f32_e32 v106, 0, v106
	v_max_f32_e32 v107, 0, v107
	v_lshl_add_u64 v[104:105], v[104:105], 0, s[8:9]
	v_pk_mul_f32 v[108:109], v[108:109], v[108:109]
	v_pk_mul_f32 v[118:119], v[106:107], v[106:107]
	v_lshl_add_u64 v[104:105], v[104:105], 0, s[0:1]
	v_pk_mul_f32 v[96:97], v[96:97], v[112:113] op_sel_hi:[1,0]
	v_lshl_add_u64 v[114:115], v[104:105], 0, v[128:129]
	v_cvt_pk_bf16_f32 v104, v108, v109
	v_cvt_pk_bf16_f32 v105, v110, v111
	v_cvt_pk_bf16_f32 v106, v116, v117
	v_cvt_pk_bf16_f32 v107, v118, v119
	v_pk_mul_f32 v[102:103], v[102:103], v[112:113] op_sel_hi:[1,0]
	v_pk_mul_f32 v[100:101], v[100:101], v[112:113] op_sel_hi:[1,0]
	v_pk_mul_f32 v[98:99], v[98:99], v[112:113] op_sel_hi:[1,0]
	v_max_f32_e32 v96, 0, v96
	v_max_f32_e32 v97, 0, v97
	global_store_dwordx4 v[114:115], v[104:107], off
	v_max_f32_e32 v100, 0, v100
	v_max_f32_e32 v101, 0, v101
	v_pk_mul_f32 v[104:105], v[96:97], v[96:97]
	v_max_f32_e32 v96, 0, v102
	v_max_f32_e32 v98, 0, v98
	v_max_f32_e32 v97, 0, v103
	v_max_f32_e32 v99, 0, v99
	v_pk_mul_f32 v[100:101], v[100:101], v[100:101]
	v_pk_mul_f32 v[102:103], v[96:97], v[96:97]
	v_pk_mul_f32 v[106:107], v[98:99], v[98:99]
	v_cvt_pk_bf16_f32 v96, v100, v101
	v_cvt_pk_bf16_f32 v97, v102, v103
	v_cvt_pk_bf16_f32 v98, v104, v105
	v_cvt_pk_bf16_f32 v99, v106, v107
	global_store_dwordx4 v[114:115], v[96:99], off offset:64
	v_mov_b32_e32 v167, v169
	v_mov_b32_e32 v168, v171
	v_mov_b32_e32 v98, v152
	v_mov_b32_e32 v99, v150
	v_mov_b32_e32 v150, v153
	v_pk_add_f32 v[98:99], v[98:99], v[150:151]
	v_lshlrev_b64 v[96:97], 13, v[146:147]
	v_pk_fma_f32 v[98:99], v[98:99], s[4:5], v[132:133] op_sel_hi:[1,0,0]
	v_lshl_add_u64 v[96:97], s[10:11], 0, v[96:97]
	v_mul_f32_e32 v100, 0x4b800000, v99
	v_cmp_gt_f32_e32 vcc, s5, v99
	v_lshl_add_u64 v[96:97], v[96:97], 0, s[8:9]
	v_lshl_add_u64 v[96:97], v[96:97], 0, s[0:1]
	v_cndmask_b32_e32 v99, v99, v100, vcc
	v_rsq_f32_e32 v99, v99
	v_lshl_add_u64 v[96:97], v[96:97], 0, v[128:129]
	v_mov_b32_e32 v169, v172
	v_mov_b32_e32 v171, v173
	v_mul_f32_e32 v100, 0x45800000, v99
	v_cndmask_b32_e32 v100, v99, v100, vcc
	v_pk_mul_f32 v[88:89], v[88:89], v[100:101] op_sel_hi:[1,0]
	v_pk_mul_f32 v[94:95], v[94:95], v[100:101] op_sel_hi:[1,0]
	v_pk_mul_f32 v[92:93], v[92:93], v[100:101] op_sel_hi:[1,0]
	v_pk_mul_f32 v[90:91], v[90:91], v[100:101] op_sel_hi:[1,0]
	v_max_f32_e32 v88, 0, v88
	v_max_f32_e32 v89, 0, v89
	v_max_f32_e32 v92, 0, v92
	v_max_f32_e32 v93, 0, v93
	v_pk_mul_f32 v[102:103], v[88:89], v[88:89]
	v_max_f32_e32 v88, 0, v94
	v_max_f32_e32 v90, 0, v90
	v_max_f32_e32 v89, 0, v95
	v_max_f32_e32 v91, 0, v91
	v_pk_mul_f32 v[92:93], v[92:93], v[92:93]
	v_pk_mul_f32 v[94:95], v[88:89], v[88:89]
	v_pk_mul_f32 v[104:105], v[90:91], v[90:91]
	v_pk_mul_f32 v[82:83], v[82:83], v[100:101] op_sel_hi:[1,0]
	v_cvt_pk_bf16_f32 v88, v92, v93
	v_cvt_pk_bf16_f32 v89, v94, v95
	v_cvt_pk_bf16_f32 v90, v102, v103
	v_cvt_pk_bf16_f32 v91, v104, v105
	v_pk_mul_f32 v[84:85], v[84:85], v[100:101] op_sel_hi:[1,0]
	v_pk_mul_f32 v[80:81], v[80:81], v[100:101] op_sel_hi:[1,0]
	v_max_f32_e32 v82, 0, v82
	v_max_f32_e32 v83, 0, v83
	global_store_dwordx4 v[96:97], v[88:91], off
	v_pk_mul_f32 v[86:87], v[86:87], v[100:101] op_sel_hi:[1,0]
	v_max_f32_e32 v84, 0, v84
	v_max_f32_e32 v80, 0, v80
	v_max_f32_e32 v85, 0, v85
	v_max_f32_e32 v81, 0, v81
	v_pk_mul_f32 v[90:91], v[82:83], v[82:83]
	v_mul_f32_e32 v82, 0x4b800000, v98
	v_cmp_gt_f32_e32 vcc, s5, v98
	v_pk_mul_f32 v[84:85], v[84:85], v[84:85]
	v_pk_mul_f32 v[88:89], v[80:81], v[80:81]
	v_max_f32_e32 v80, 0, v86
	v_max_f32_e32 v81, 0, v87
	v_cndmask_b32_e32 v82, v98, v82, vcc
	v_pk_mul_f32 v[86:87], v[80:81], v[80:81]
	v_cvt_pk_bf16_f32 v80, v84, v85
	v_rsq_f32_e32 v84, v82
	v_cvt_pk_bf16_f32 v81, v86, v87
	v_cvt_pk_bf16_f32 v82, v88, v89
	v_cvt_pk_bf16_f32 v83, v90, v91
	global_store_dwordx4 v[96:97], v[80:83], off offset:64
	v_pk_add_f32 v[134:135], v[164:165], v[166:167]
	v_pk_add_f32 v[136:137], v[168:169], v[170:171]
	v_mul_f32_e32 v80, 0x45800000, v84
	v_cndmask_b32_e32 v80, v84, v80, vcc
	v_pk_mul_f32 v[72:73], v[72:73], v[80:81] op_sel_hi:[1,0]
	v_pk_mul_f32 v[78:79], v[78:79], v[80:81] op_sel_hi:[1,0]
	v_max_f32_e32 v72, 0, v72
	v_max_f32_e32 v73, 0, v73
	v_lshlrev_b64 v[82:83], 13, v[140:141]
	v_pk_mul_f32 v[84:85], v[72:73], v[72:73]
	v_max_f32_e32 v72, 0, v78
	v_max_f32_e32 v73, 0, v79
	v_pk_mul_f32 v[76:77], v[76:77], v[80:81] op_sel_hi:[1,0]
	v_pk_mul_f32 v[74:75], v[74:75], v[80:81] op_sel_hi:[1,0]
	v_pk_mul_f32 v[78:79], v[72:73], v[72:73]
	v_lshl_add_u64 v[72:73], s[10:11], 0, v[82:83]
	v_max_f32_e32 v76, 0, v76
	v_max_f32_e32 v77, 0, v77
	v_max_f32_e32 v74, 0, v74
	v_max_f32_e32 v75, 0, v75
	v_lshl_add_u64 v[72:73], v[72:73], 0, s[8:9]
	v_pk_mul_f32 v[76:77], v[76:77], v[76:77]
	v_pk_mul_f32 v[86:87], v[74:75], v[74:75]
	v_lshl_add_u64 v[72:73], v[72:73], 0, s[0:1]
	v_pk_mul_f32 v[64:65], v[64:65], v[80:81] op_sel_hi:[1,0]
;     __device__ __forceinline__ void operator()(const f32x4 (&acc)[2][2][4][2], const Unit& u, int wr, int wc, int fr, int fq) const {
;     ...
;         for (int idx = 0; idx < 8; ++idx) { const f32x4 q = *(const f32x4*)(rowss + (size_t)(u.pm * BM + (idx >> 2) * HALF + wr * 64 + (idx & 3) * 16 + fr) * 4); rsv[idx] = (q[0] + q[1]) + (q[2] + q[3]); }
; #pragma unroll
;         for (int ai = 0; ai < 2; ++ai)
; #pragma unroll
;             for (int m = 0; m < 4; ++m) {
;                 const int r = u.pm * BM + ai * HALF + wr * 64 + m * 16 + fr;
;                 const float rs = rsqrtf(rsv[ai * 4 + m] * (1.0f / DM) + EPS);
; #pragma unroll
;                 for (int bj = 0; bj < 2; ++bj) {
;                     f32x4 a = acc[ai][bj][m][0] * rs, b = acc[ai][bj][m][1] * rs;
; #pragma unroll
;                     for (int t = 0; t < 4; ++t) { a[t] = fmaxf(a[t], 0.f); a[t] *= a[t]; b[t] = fmaxf(b[t], 0.f); b[t] *= b[t]; }
;                     st8bf(U + (size_t)r * FF + u.pn * BM + wc * 64 + bj * 32 + 8 * fq, a, b);
;                 }
;             }
	v_lshl_add_u64 v[82:83], v[72:73], 0, v[128:129]
	v_cvt_pk_bf16_f32 v72, v76, v77
	v_cvt_pk_bf16_f32 v73, v78, v79
	v_cvt_pk_bf16_f32 v74, v84, v85
	v_cvt_pk_bf16_f32 v75, v86, v87
	v_pk_mul_f32 v[70:71], v[70:71], v[80:81] op_sel_hi:[1,0]
	v_pk_mul_f32 v[68:69], v[68:69], v[80:81] op_sel_hi:[1,0]
	v_pk_mul_f32 v[66:67], v[66:67], v[80:81] op_sel_hi:[1,0]
	v_max_f32_e32 v64, 0, v64
	v_max_f32_e32 v65, 0, v65
	global_store_dwordx4 v[82:83], v[72:75], off
	v_max_f32_e32 v68, 0, v68
	v_max_f32_e32 v69, 0, v69
	v_pk_mul_f32 v[72:73], v[64:65], v[64:65]
	v_max_f32_e32 v64, 0, v70
	v_max_f32_e32 v66, 0, v66
	v_max_f32_e32 v65, 0, v71
	v_max_f32_e32 v67, 0, v67
	v_pk_mul_f32 v[68:69], v[68:69], v[68:69]
	v_pk_mul_f32 v[70:71], v[64:65], v[64:65]
	v_pk_mul_f32 v[74:75], v[66:67], v[66:67]
	v_cvt_pk_bf16_f32 v64, v68, v69
	v_cvt_pk_bf16_f32 v65, v70, v71
	v_cvt_pk_bf16_f32 v66, v72, v73
	v_cvt_pk_bf16_f32 v67, v74, v75
	global_store_dwordx4 v[82:83], v[64:67], off offset:64
	s_nop 1
	v_mov_b32_e32 v66, v144
	v_mov_b32_e32 v67, v142
	v_mov_b32_e32 v142, v145
	v_pk_add_f32 v[66:67], v[66:67], v[142:143]
	v_lshlrev_b64 v[64:65], 13, v[138:139]
	v_pk_fma_f32 v[66:67], v[66:67], s[4:5], v[132:133] op_sel_hi:[1,0,0]
	v_lshl_add_u64 v[64:65], s[10:11], 0, v[64:65]
	v_mul_f32_e32 v68, 0x4b800000, v67
	v_cmp_gt_f32_e32 vcc, s5, v67
	v_lshl_add_u64 v[64:65], v[64:65], 0, s[8:9]
	v_lshl_add_u64 v[64:65], v[64:65], 0, s[0:1]
	v_cndmask_b32_e32 v67, v67, v68, vcc
	v_rsq_f32_e32 v67, v67
	v_lshl_add_u64 v[64:65], v[64:65], 0, v[128:129]
	s_mov_b32 s0, 0x120000
	v_mul_f32_e32 v68, 0x45800000, v67
	v_cndmask_b32_e32 v68, v67, v68, vcc
	v_pk_mul_f32 v[56:57], v[56:57], v[68:69] op_sel_hi:[1,0]
	v_pk_mul_f32 v[62:63], v[62:63], v[68:69] op_sel_hi:[1,0]
	v_pk_mul_f32 v[60:61], v[60:61], v[68:69] op_sel_hi:[1,0]
	v_pk_mul_f32 v[58:59], v[58:59], v[68:69] op_sel_hi:[1,0]
	v_max_f32_e32 v56, 0, v56
	v_max_f32_e32 v57, 0, v57
	v_max_f32_e32 v60, 0, v60
	v_max_f32_e32 v61, 0, v61
	v_pk_mul_f32 v[70:71], v[56:57], v[56:57]
	v_max_f32_e32 v56, 0, v62
	v_max_f32_e32 v58, 0, v58
	v_max_f32_e32 v57, 0, v63
	v_max_f32_e32 v59, 0, v59
	v_pk_mul_f32 v[60:61], v[60:61], v[60:61]
	v_pk_mul_f32 v[62:63], v[56:57], v[56:57]
	v_pk_mul_f32 v[72:73], v[58:59], v[58:59]
	v_pk_mul_f32 v[50:51], v[50:51], v[68:69] op_sel_hi:[1,0]
	v_cvt_pk_bf16_f32 v56, v60, v61
	v_cvt_pk_bf16_f32 v57, v62, v63
	v_cvt_pk_bf16_f32 v58, v70, v71
	v_cvt_pk_bf16_f32 v59, v72, v73
	v_pk_mul_f32 v[52:53], v[52:53], v[68:69] op_sel_hi:[1,0]
	v_pk_mul_f32 v[48:49], v[48:49], v[68:69] op_sel_hi:[1,0]
	v_max_f32_e32 v50, 0, v50
	v_max_f32_e32 v51, 0, v51
	global_store_dwordx4 v[64:65], v[56:59], off
	v_pk_mul_f32 v[54:55], v[54:55], v[68:69] op_sel_hi:[1,0]
	v_max_f32_e32 v52, 0, v52
	v_max_f32_e32 v48, 0, v48
	v_max_f32_e32 v53, 0, v53
	v_max_f32_e32 v49, 0, v49
	v_pk_mul_f32 v[58:59], v[50:51], v[50:51]
	v_mul_f32_e32 v50, 0x4b800000, v66
	v_cmp_gt_f32_e32 vcc, s5, v66
	v_pk_mul_f32 v[52:53], v[52:53], v[52:53]
	v_pk_mul_f32 v[56:57], v[48:49], v[48:49]
	v_max_f32_e32 v48, 0, v54
	v_max_f32_e32 v49, 0, v55
	v_cndmask_b32_e32 v50, v66, v50, vcc
	v_pk_mul_f32 v[54:55], v[48:49], v[48:49]
	v_cvt_pk_bf16_f32 v48, v52, v53
	v_rsq_f32_e32 v52, v50
	v_cvt_pk_bf16_f32 v49, v54, v55
	v_cvt_pk_bf16_f32 v50, v56, v57
	v_cvt_pk_bf16_f32 v51, v58, v59
	global_store_dwordx4 v[64:65], v[48:51], off offset:64
	v_lshl_add_u64 v[54:55], v[130:131], 0, s[6:7]
	s_mov_b64 s[6:7], 0x140000
	v_mul_f32_e32 v48, 0x45800000, v52
	v_cndmask_b32_e32 v48, v52, v48, vcc
	v_pk_mul_f32 v[44:45], v[44:45], v[48:49] op_sel_hi:[1,0]
	v_pk_mul_f32 v[40:41], v[40:41], v[48:49] op_sel_hi:[1,0]
	v_pk_mul_f32 v[46:47], v[46:47], v[48:49] op_sel_hi:[1,0]
	v_pk_mul_f32 v[42:43], v[42:43], v[48:49] op_sel_hi:[1,0]
	v_max_f32_e32 v44, 0, v44
	v_max_f32_e32 v40, 0, v40
	v_max_f32_e32 v45, 0, v45
	v_max_f32_e32 v41, 0, v41
	v_pk_mul_f32 v[44:45], v[44:45], v[44:45]
	v_pk_mul_f32 v[50:51], v[40:41], v[40:41]
	v_max_f32_e32 v40, 0, v46
	v_max_f32_e32 v42, 0, v42
	v_max_f32_e32 v41, 0, v47
	v_max_f32_e32 v43, 0, v43
	v_pk_mul_f32 v[46:47], v[40:41], v[40:41]
	v_pk_mul_f32 v[52:53], v[42:43], v[42:43]
	v_cvt_pk_bf16_f32 v40, v44, v45
	v_add_co_u32_e32 v44, vcc, s0, v130
	v_pk_mul_f32 v[32:33], v[32:33], v[48:49] op_sel_hi:[1,0]
	v_cvt_pk_bf16_f32 v41, v46, v47
	v_cvt_pk_bf16_f32 v42, v50, v51
	v_cvt_pk_bf16_f32 v43, v52, v53
	v_addc_co_u32_e32 v45, vcc, 0, v131, vcc
	v_pk_mul_f32 v[38:39], v[38:39], v[48:49] op_sel_hi:[1,0]
	v_pk_mul_f32 v[36:37], v[36:37], v[48:49] op_sel_hi:[1,0]
	v_pk_mul_f32 v[34:35], v[34:35], v[48:49] op_sel_hi:[1,0]
	v_max_f32_e32 v32, 0, v32
	v_max_f32_e32 v33, 0, v33
	global_store_dwordx4 v[44:45], v[40:43], off
	v_max_f32_e32 v36, 0, v36
	v_max_f32_e32 v37, 0, v37
	v_pk_mul_f32 v[40:41], v[32:33], v[32:33]
	v_max_f32_e32 v32, 0, v38
	v_max_f32_e32 v34, 0, v34
	v_max_f32_e32 v33, 0, v39
	v_max_f32_e32 v35, 0, v35
	v_pk_mul_f32 v[36:37], v[36:37], v[36:37]
	v_pk_mul_f32 v[38:39], v[32:33], v[32:33]
	v_pk_mul_f32 v[42:43], v[34:35], v[34:35]
	v_cvt_pk_bf16_f32 v32, v36, v37
	v_cvt_pk_bf16_f32 v33, v38, v39
	v_cvt_pk_bf16_f32 v34, v40, v41
	v_cvt_pk_bf16_f32 v35, v42, v43
	global_store_dwordx4 v[54:55], v[32:35], off offset:64
	s_mov_b32 s0, 0x140000
	s_nop 0
	v_mov_b32_e32 v32, v136
	v_mov_b32_e32 v33, v134
	v_mov_b32_e32 v134, v137
	v_pk_add_f32 v[32:33], v[32:33], v[134:135]
	s_nop 0
	v_pk_fma_f32 v[32:33], v[32:33], s[4:5], v[132:133] op_sel_hi:[1,0,0]
	s_nop 0
	v_mul_f32_e32 v34, 0x4b800000, v33
	v_cmp_gt_f32_e32 vcc, s5, v33
	s_nop 1
	v_cndmask_b32_e32 v33, v33, v34, vcc
	v_rsq_f32_e32 v33, v33
	v_lshl_add_u64 v[34:35], v[130:131], 0, s[6:7]
;     __device__ __forceinline__ void operator()(const f32x4 (&acc)[2][2][4][2], const Unit& u, int wr, int wc, int fr, int fq) const {
;     ...
;         for (int ai = 0; ai < 2; ++ai)
; #pragma unroll
;             for (int m = 0; m < 4; ++m) {
;                 const int r = u.pm * BM + ai * HALF + wr * 64 + m * 16 + fr;
;                 const float rs = rsqrtf(rsv[ai * 4 + m] * (1.0f / DM) + EPS);
; #pragma unroll
;                 for (int bj = 0; bj < 2; ++bj) {
;                     f32x4 a = acc[ai][bj][m][0] * rs, b = acc[ai][bj][m][1] * rs;
; #pragma unroll
;                     for (int t = 0; t < 4; ++t) { a[t] = fmaxf(a[t], 0.f); a[t] *= a[t]; b[t] = fmaxf(b[t], 0.f); b[t] *= b[t]; }
;                     st8bf(U + (size_t)r * FF + u.pn * BM + wc * 64 + bj * 32 + 8 * fq, a, b);
;                 }
;             }
; DI void retout_load(const Params& P, int ru, int tid, int wave, int lane, OutRegs& R) {
;     const bf16_t* Z = (const bf16_t*)(P.ws + WS_Z);
;     bool samp; int b, c, h, row0; ret_decode(ru, samp, b, c, h, row0);
; #pragma unroll
;     for (int i = 0; i < 2; ++i) { const int v = tid + 512 * i, j = v >> 4, d0 = (v & 15) * 8; const bf16_t* zr = Z + (size_t)(row0 + j) * INW;
;         R.q[i] = __builtin_nontemporal_load((const u32x4*)(zr + 768 + 128 * h + d0)); R.k[i] = __builtin_nontemporal_load((const u32x4*)(zr + 1280 + 128 * h + d0)); R.v[i] = __builtin_nontemporal_load((const u32x4*)(zr + 1792 + 128 * h + d0)); }
;     const bf16_t* S = (const bf16_t*)(P.ws + WS_SB) + ((size_t)(b * 32 + (c > 0 ? c - 1 : 0)) * 4 + h) * 16384;
; #pragma unroll
;     for (int i = 0; i < 4; ++i) { const int v = tid + 512 * i, dk = v >> 4, e0 = (v & 15) * 8; R.s[i] = (u32x4){0u, 0u, 0u, 0u}; if (c > 0) R.s[i] = __builtin_nontemporal_load((const u32x4*)(S + dk * 128 + e0)); }
;     const int g = lane >> 4, i_ = 16 * (wave & 3) + (lane & 15), eh = wave >> 2;
; #pragma unroll
;     for (int et = 0; et < 4; ++et) R.gt[et] = *(const u32x2*)(Z + (size_t)(row0 + i_) * INW + 2304 + 128 * h + 64 * eh + 16 * et + 4 * g);
; }
	v_mul_f32_e32 v36, 0x45800000, v33
	v_cndmask_b32_e32 v36, v33, v36, vcc
	v_pk_mul_f32 v[28:29], v[28:29], v[36:37] op_sel_hi:[1,0]
	v_pk_mul_f32 v[24:25], v[24:25], v[36:37] op_sel_hi:[1,0]
	v_pk_mul_f32 v[30:31], v[30:31], v[36:37] op_sel_hi:[1,0]
	v_pk_mul_f32 v[26:27], v[26:27], v[36:37] op_sel_hi:[1,0]
	v_max_f32_e32 v28, 0, v28
	v_max_f32_e32 v24, 0, v24
	v_max_f32_e32 v29, 0, v29
	v_max_f32_e32 v25, 0, v25
	v_pk_mul_f32 v[28:29], v[28:29], v[28:29]
	v_pk_mul_f32 v[38:39], v[24:25], v[24:25]
	v_max_f32_e32 v24, 0, v30
	v_max_f32_e32 v26, 0, v26
	v_max_f32_e32 v25, 0, v31
	v_max_f32_e32 v27, 0, v27
	v_pk_mul_f32 v[30:31], v[24:25], v[24:25]
	v_pk_mul_f32 v[40:41], v[26:27], v[26:27]
	v_cvt_pk_bf16_f32 v24, v28, v29
	v_add_co_u32_e32 v28, vcc, s0, v130
	v_pk_mul_f32 v[18:19], v[18:19], v[36:37] op_sel_hi:[1,0]
	v_cvt_pk_bf16_f32 v25, v30, v31
	v_cvt_pk_bf16_f32 v26, v38, v39
	v_cvt_pk_bf16_f32 v27, v40, v41
	v_addc_co_u32_e32 v29, vcc, 0, v131, vcc
	v_pk_mul_f32 v[20:21], v[20:21], v[36:37] op_sel_hi:[1,0]
	v_pk_mul_f32 v[16:17], v[16:17], v[36:37] op_sel_hi:[1,0]
	v_max_f32_e32 v18, 0, v18
	v_max_f32_e32 v19, 0, v19
	global_store_dwordx4 v[28:29], v[24:27], off
	v_pk_mul_f32 v[22:23], v[22:23], v[36:37] op_sel_hi:[1,0]
	v_max_f32_e32 v20, 0, v20
	v_max_f32_e32 v16, 0, v16
	v_max_f32_e32 v21, 0, v21
	v_max_f32_e32 v17, 0, v17
	v_pk_mul_f32 v[26:27], v[18:19], v[18:19]
	v_mul_f32_e32 v18, 0x4b800000, v32
	v_cmp_gt_f32_e32 vcc, s5, v32
	v_pk_mul_f32 v[20:21], v[20:21], v[20:21]
	v_pk_mul_f32 v[24:25], v[16:17], v[16:17]
	v_max_f32_e32 v16, 0, v22
	v_max_f32_e32 v17, 0, v23
	v_cndmask_b32_e32 v18, v32, v18, vcc
	v_pk_mul_f32 v[22:23], v[16:17], v[16:17]
	v_cvt_pk_bf16_f32 v16, v20, v21
	v_rsq_f32_e32 v20, v18
	v_cvt_pk_bf16_f32 v17, v22, v23
	v_cvt_pk_bf16_f32 v18, v24, v25
	v_cvt_pk_bf16_f32 v19, v26, v27
	global_store_dwordx4 v[34:35], v[16:19], off offset:64
	s_mov_b32 s0, 0x160000
	s_mov_b64 s[4:5], 0x160000
	v_mul_f32_e32 v16, 0x45800000, v20
	v_cndmask_b32_e32 v16, v20, v16, vcc
	v_pk_mul_f32 v[12:13], v[12:13], v[16:17] op_sel_hi:[1,0]
	v_pk_mul_f32 v[8:9], v[8:9], v[16:17] op_sel_hi:[1,0]
	v_pk_mul_f32 v[14:15], v[14:15], v[16:17] op_sel_hi:[1,0]
	v_pk_mul_f32 v[10:11], v[10:11], v[16:17] op_sel_hi:[1,0]
	v_max_f32_e32 v12, 0, v12
	v_max_f32_e32 v8, 0, v8
	v_max_f32_e32 v13, 0, v13
	v_max_f32_e32 v9, 0, v9
	v_pk_mul_f32 v[12:13], v[12:13], v[12:13]
	v_pk_mul_f32 v[18:19], v[8:9], v[8:9]
	v_max_f32_e32 v8, 0, v14
	v_max_f32_e32 v10, 0, v10
	v_max_f32_e32 v9, 0, v15
	v_max_f32_e32 v11, 0, v11
	v_pk_mul_f32 v[14:15], v[8:9], v[8:9]
	v_pk_mul_f32 v[20:21], v[10:11], v[10:11]
	v_cvt_pk_bf16_f32 v8, v12, v13
	v_add_co_u32_e32 v12, vcc, s0, v130
	v_pk_mul_f32 v[0:1], v[0:1], v[16:17] op_sel_hi:[1,0]
	v_cvt_pk_bf16_f32 v9, v14, v15
	v_cvt_pk_bf16_f32 v10, v18, v19
	v_cvt_pk_bf16_f32 v11, v20, v21
	v_addc_co_u32_e32 v13, vcc, 0, v131, vcc
	v_pk_mul_f32 v[6:7], v[6:7], v[16:17] op_sel_hi:[1,0]
	v_pk_mul_f32 v[4:5], v[4:5], v[16:17] op_sel_hi:[1,0]
	v_pk_mul_f32 v[2:3], v[2:3], v[16:17] op_sel_hi:[1,0]
	v_max_f32_e32 v0, 0, v0
	v_max_f32_e32 v1, 0, v1
	global_store_dwordx4 v[12:13], v[8:11], off
	v_max_f32_e32 v4, 0, v4
	v_max_f32_e32 v5, 0, v5
	v_pk_mul_f32 v[8:9], v[0:1], v[0:1]
	v_max_f32_e32 v0, 0, v6
	v_max_f32_e32 v2, 0, v2
	v_max_f32_e32 v1, 0, v7
	v_max_f32_e32 v3, 0, v3
	v_pk_mul_f32 v[4:5], v[4:5], v[4:5]
	v_pk_mul_f32 v[6:7], v[0:1], v[0:1]
	v_pk_mul_f32 v[10:11], v[2:3], v[2:3]
	v_lshl_add_u64 v[22:23], v[130:131], 0, s[4:5]
	v_cvt_pk_bf16_f32 v0, v4, v5
	v_cvt_pk_bf16_f32 v1, v6, v7
	v_cvt_pk_bf16_f32 v2, v8, v9
	v_cvt_pk_bf16_f32 v3, v10, v11
	global_store_dwordx4 v[22:23], v[0:3], off offset:64
	s_waitcnt vmcnt(0)
	s_sub_i32 s0, s2, s49
	v_mov_b32_e32 v41, v175
	s_cmp_lt_u32 s0, 0x7ffffc00
	s_barrier
	s_cbranch_scc1 .LBB0_786
	s_add_i32 s54, s0, 0x400
	s_ashr_i32 s7, s54, 7
	s_bfe_u32 s8, s0, 0x50002
	s_lshl_b32 s0, s7, 11
	s_lshl_b32 s4, s8, 6
	s_or_b32 s6, s4, s0
	v_ashrrev_i32_e32 v118, 4, v41
	v_add_u32_e32 v10, 0x200, v41
	s_and_b32 s10, s2, 3
	v_lshlrev_b32_e32 v34, 3, v41
	v_add_u32_e32 v0, s6, v118
	s_movk_i32 s9, 0x1600
	v_mov_b64_e32 v[8:9], s[74:75]
	v_ashrrev_i32_e32 v119, 4, v10
	v_and_b32_e32 v2, 0x78, v34
	v_mad_i64_i32 v[0:1], s[4:5], v0, s9, v[8:9]
	s_lshl_b32 s0, s10, 8
	v_add_u32_e32 v10, s6, v119
	v_lshl_add_u64 v[0:1], v[0:1], 0, s[0:1]
	v_lshlrev_b32_e32 v128, 1, v2
	v_mad_i64_i32 v[8:9], s[4:5], v10, s9, v[8:9]
	v_lshl_add_u64 v[24:25], v[0:1], 0, v[128:129]
	v_lshl_add_u64 v[8:9], v[8:9], 0, s[0:1]
	global_load_dwordx4 v[0:3], v[24:25], off offset:1536 nt
	global_load_dwordx4 v[4:7], v[24:25], off offset:2560 nt
	v_lshl_add_u64 v[26:27], v[8:9], 0, v[128:129]
	global_load_dwordx4 v[8:11], v[24:25], off offset:3584 nt
	global_load_dwordx4 v[12:15], v[26:27], off offset:1536 nt
	global_load_dwordx4 v[16:19], v[26:27], off offset:2560 nt
	global_load_dwordx4 v[20:23], v[26:27], off offset:3584 nt
	s_lshl_b32 s0, s7, 5
	s_max_u32 s1, s8, 1
	s_or_b32 s0, s0, s1
	s_add_i32 s0, s0, -1
	s_ashr_i32 s1, s0, 31
	s_lshl_b64 s[0:1], s[0:1], 17
	s_add_u32 s0, s46, s0
	s_addc_u32 s1, s3, s1
	s_lshl_b32 s11, s10, 15
	s_add_u32 s4, s0, s11
	s_addc_u32 s5, s1, 0
	s_cmp_lg_u32 s8, 0
	s_cselect_b64 s[0:1], -1, 0
	v_lshl_add_u64 v[32:33], s[4:5], 0, v[128:129]
	s_and_b64 vcc, exec, s[0:1]
	s_cbranch_vccz .LBB0_833
	v_and_b32_e32 v68, 0xffffff80, v34
	v_add_u32_e32 v24, 0x1000, v68
	v_ashrrev_i32_e32 v69, 31, v68
	v_ashrrev_i32_e32 v25, 31, v24
	v_lshl_add_u64 v[38:39], v[68:69], 1, v[32:33]
	v_lshl_add_u64 v[36:37], v[24:25], 1, v[32:33]
	global_load_dwordx4 v[28:31], v[38:39], off nt
	global_load_dwordx4 v[24:27], v[36:37], off nt
	s_cbranch_execnz .LBB0_765
